# phase 0: w_in transpose tile issues its four row loads together (counted vmcnt) instead of load-wait four times
# baseline (speedup 1.0000x reference)
; __device__ __forceinline__ float ozero() { float z = 0.f; asm volatile("" : "+v"(z)); return z; }
; __device__ __forceinline__ bf f2bf(float f) { return (bf)(pk2(f, 0.f) & 0xFFFFu); }
; __device__ __forceinline__ void transpose_tile(const float* __restrict__ src, int R, int C, bf* __restrict__ dst, int ldd, int off, int tile, bf* sm) {
;     ...
;   for (int i = 0; i < 4; i++) {
;     int r = (tid >> 4) + 16 * i; int c = (tid & 15) * 4;
;     const float zt_ = ozero(); float4 v = make_float4(zt_, zt_, zt_, zt_);
;     if (c0 + c < C) v = *(const float4*)(src + (size_t)(r0 + r) * C + c0 + c);
;     sm[(c + 0) * 66 + r] = f2bf(v.x); sm[(c + 1) * 66 + r] = f2bf(v.y);
;     sm[(c + 2) * 66 + r] = f2bf(v.z); sm[(c + 3) * 66 + r] = f2bf(v.w);
;   }
;   __syncthreads();
;   {
;     int c = tid >> 2, ch = (tid & 3) * 16;
;     if (c0 + c < C) {
;       unsigned wv[8];
; #pragma unroll
;       for (int k = 0; k < 8; k++) wv[k] = *(const unsigned*)(sm + c * 66 + ch + 2 * k);
;       bf* d = dst + (size_t)(c0 + c) * ldd + off + r0 + ch;
;       *(uint4*)d = make_uint4(wv[0], wv[1], wv[2], wv[3]);
;       *(uint4*)(d + 8) = make_uint4(wv[4], wv[5], wv[6], wv[7]);
;     }
.LBB0_8:
	s_load_dwordx16 s[36:51], s[0:1], 0x0
	s_mul_i32 s7, s2, 0x6ca8000
	s_mul_hi_i32 s6, s2, 0x6ca8000
	v_mov_b32_e32 v11, v203
	s_waitcnt lgkmcnt(0)
	s_add_u32 s7, s42, s7
	s_addc_u32 s13, s43, s6
	s_mul_hi_i32 s6, s12, 0x964fda6d
	s_add_i32 s6, s6, s12
	s_lshr_b32 s8, s6, 31
	s_ashr_i32 s6, s6, 7
	s_add_i32 s6, s6, s8
	s_mul_i32 s8, s6, 0xffffff26
	s_add_i32 s8, s12, s8
	s_lshl_b32 s8, s8, 6
	v_lshlrev_b32_e32 v2, 2, v11
	s_ashr_i32 s9, s8, 31
	s_lshl_b32 s6, s6, 6
	v_and_b32_e32 v13, 60, v2
	s_lshl_b64 s[10:11], s[8:9], 2
	v_or_b32_e32 v2, s8, v13
	s_add_u32 s10, s7, s10
	v_cmp_gt_i32_e32 vcc, s19, v2
	s_addc_u32 s11, s13, s11
	v_lshlrev_b32_e32 v6, 2, v13
	v_bfe_u32 v12, v11, 4, 4
	v_lshl_add_u64 v[8:9], s[10:11], 0, v[6:7]
	v_mov_b32_e32 v72, 0
	v_mov_b32_e32 v73, 0
	v_mov_b32_e32 v74, 0
	v_mov_b32_e32 v75, 0
	v_mov_b32_e32 v76, 0
	v_mov_b32_e32 v77, 0
	v_mov_b32_e32 v78, 0
	v_mov_b32_e32 v79, 0
	v_mov_b32_e32 v80, 0
	v_mov_b32_e32 v81, 0
	v_mov_b32_e32 v82, 0
	v_mov_b32_e32 v83, 0
	v_mov_b32_e32 v84, 0
	v_mov_b32_e32 v85, 0
	v_mov_b32_e32 v86, 0
	v_mov_b32_e32 v87, 0
	s_and_saveexec_b64 s[10:11], vcc
	s_cbranch_execz .Lp0_skip
	v_or_b32_e32 v88, s6, v12
	v_mad_i64_i32 v[88:89], s[14:15], v88, s20, v[8:9]
	global_load_dwordx4 v[72:75], v[88:89], off
	v_or3_b32 v90, v12, s6, 16
	v_mad_i64_i32 v[90:91], s[14:15], v90, s20, v[8:9]
	global_load_dwordx4 v[76:79], v[90:91], off
	v_or3_b32 v88, v12, s6, 32
	v_mad_i64_i32 v[88:89], s[14:15], v88, s20, v[8:9]
	global_load_dwordx4 v[80:83], v[88:89], off
	v_or3_b32 v90, v12, s6, 48
	v_mad_i64_i32 v[90:91], s[14:15], v90, s20, v[8:9]
	global_load_dwordx4 v[84:87], v[90:91], off
.Lp0_skip:
	s_or_b64 exec, exec, s[10:11]
	v_mul_u32_u24_e32 v6, 0x84, v13
	v_lshlrev_b32_e32 v13, 1, v12
	v_add3_u32 v6, s17, v6, v13
	s_waitcnt vmcnt(3)
	v_cvt_pk_bf16_f32 v2, v72, s0
	ds_write_b16 v6, v2
	v_cvt_pk_bf16_f32 v2, v73, s0
	ds_write_b16 v6, v2 offset:132
	v_cvt_pk_bf16_f32 v2, v74, s0
	ds_write_b16 v6, v2 offset:264
	v_cvt_pk_bf16_f32 v2, v75, s0
	ds_write_b16 v6, v2 offset:396
	s_waitcnt vmcnt(2)
	v_cvt_pk_bf16_f32 v2, v76, s0
	ds_write_b16 v6, v2 offset:32
	v_cvt_pk_bf16_f32 v2, v77, s0
	ds_write_b16 v6, v2 offset:164
	v_cvt_pk_bf16_f32 v2, v78, s0
	ds_write_b16 v6, v2 offset:296
	v_cvt_pk_bf16_f32 v2, v79, s0
	ds_write_b16 v6, v2 offset:428
	s_waitcnt vmcnt(1)
	v_cvt_pk_bf16_f32 v2, v80, s0
	ds_write_b16 v6, v2 offset:64
	v_cvt_pk_bf16_f32 v2, v81, s0
	ds_write_b16 v6, v2 offset:196
	v_cvt_pk_bf16_f32 v2, v82, s0
	ds_write_b16 v6, v2 offset:328
	v_cvt_pk_bf16_f32 v2, v83, s0
	ds_write_b16 v6, v2 offset:460
	s_waitcnt vmcnt(0)
	v_cvt_pk_bf16_f32 v2, v84, s0
	ds_write_b16 v6, v2 offset:96
	v_cvt_pk_bf16_f32 v2, v85, s0
	ds_write_b16 v6, v2 offset:228
	v_cvt_pk_bf16_f32 v2, v86, s0
	ds_write_b16 v6, v2 offset:360
	v_cvt_pk_bf16_f32 v2, v87, s0
	ds_write_b16 v6, v2 offset:492
	v_lshrrev_b32_sdwa v3, v1, v11 dst_sel:DWORD dst_unused:UNUSED_PAD src0_sel:DWORD src1_sel:BYTE_0
	v_or_b32_e32 v2, s8, v3
	v_cmp_gt_i32_e32 vcc, s19, v2
	s_waitcnt lgkmcnt(0)
	s_barrier
	s_and_saveexec_b64 s[8:9], vcc
	s_cbranch_execz .LBB0_18
	s_load_dwordx16 s[36:51], s[0:1], 0xc0
	v_lshlrev_b32_sdwa v4, v10, v11 dst_sel:DWORD dst_unused:UNUSED_PAD src0_sel:DWORD src1_sel:BYTE_0
	s_mul_i32 s10, s2, 0x3654000
	v_mul_u32_u24_e32 v3, 0x84, v3
	v_and_b32_e32 v6, 0x60, v4
	s_mul_hi_i32 s7, s2, 0x3654000
	s_waitcnt lgkmcnt(0)
	s_add_u32 s10, s48, s10
	v_add3_u32 v11, s17, v3, v6
	v_ashrrev_i32_e32 v3, 31, v2
	s_addc_u32 s11, s49, s7
	v_lshlrev_b64 v[2:3], 12, v[2:3]
	v_lshl_add_u64 v[8:9], s[10:11], 0, v[2:3]
	ds_read2_b32 v[2:3], v11 offset1:1
	ds_read2_b32 v[4:5], v11 offset0:2 offset1:3
	ds_read2_b32 v[12:13], v11 offset0:4 offset1:5
	ds_read2_b32 v[14:15], v11 offset0:6 offset1:7
	s_ashr_i32 s7, s6, 31
	v_lshl_add_u64 v[8:9], s[6:7], 1, v[8:9]
	v_lshl_add_u64 v[8:9], v[8:9], 0, v[6:7]
	s_waitcnt lgkmcnt(2)
	global_store_dwordx4 v[8:9], v[2:5], off
	s_waitcnt lgkmcnt(0)
	global_store_dwordx4 v[8:9], v[12:15], off offset:16
